# P2 NA: the unit's 4 gate loads issued at the unit top (into free v242..v249) instead of two thirds into the unit; the output scaling waits once
# speedup vs baseline: 1.0162x; 1.0162x over previous
; #define LAS __attribute__((address_space(3)))
; __device__ __forceinline__ f32x4 mfma16(bf16x8 a, bf16x8 b, f32x4 c) { return __builtin_amdgcn_mfma_f32_16x16x32_bf16(a, b, c, 0, 0, 0); }
; __device__ __forceinline__ void na_strip(const Params& P, LAS unsigned char* lds, int strip, int hsel, int tid, int lane, int wave) {
;     ...
;         const int r = r0 + 2 * pi, myr = r + rsel;
;         const size_t tq = (size_t)sq0 + (size_t)myr * 64 + qc;
;         const int lo = na_start(r, rows), lon = na_start(r + 2, rows);
;         const int nr0 = lo + 9, nr1 = lo + 10;
;         const bool need0 = (pi < npairs - 1) && (nr0 < lon + 9) && (nr0 < rows), need1 = (pi < npairs - 1) && (nr1 < lon + 9) && (nr1 < rows);
;         u32x4 nk0, nv0, nk1, nv1;
;         if (need0) { const size_t o = ((size_t)sq0 + (size_t)nr0 * 64) * 512 + ssrc; nk0 = *(const u32x4*)(KA + o); nv0 = *(const u32x4*)(VA + o); }
;         if (need1) { const size_t o = ((size_t)sq0 + (size_t)nr1 * 64) * 512 + ssrc; nk1 = *(const u32x4*)(KA + o); nv1 = *(const u32x4*)(VA + o); }
;         bf16x8 qn[2];
;         if (pi < npairs - 1) {
; #pragma unroll
;             for (int ks = 0; ks < 2; ++ks) qn[ks] = *(const bf16x8*)(QA + (tq + 128) * 512 + h * 64 + 32 * ks + 8 * g); }
;         u32x2 gv[4];
; #pragma unroll
;         for (int dt = 0; dt < 4; ++dt) gv[dt] = *(const u32x2*)(GA + tq * 512 + h * 64 + 16 * dt + 4 * g);
;         const int start = na_start(myr, rows);
;         f32x4 sc[8][2];
; #pragma unroll
;         for (int j = 0; j < 8; ++j) { const LAS float* rpj = rp + (start + j - myr + 7) * 31;
; #pragma unroll
;             for (int kt = 0; kt < 2; ++kt)
; #pragma unroll
;                 for (int i = 0; i < 4; ++i) sc[j][kt][i] = rpj[bofs[kt][i]] + msk[kt][i]; }
; #pragma unroll
;         for (int j = 0; j < 8; ++j) { const LAS unsigned char* kt_ = lds + NA_KR + (unsigned)((start + j) % 9) * 8192u;
; #pragma unroll
;             for (int kt = 0; kt < 2; ++kt) { const unsigned key = kstart + 16 * kt + l15; const LAS unsigned char* kp = kt_ + key * 128;
;                 f32x4 a = sc[j][kt];
;                 a = mfma16(*(const LAS bf16x8*)(kp + 16 * ((unsigned)g ^ (key & 7))), qf[0], a);
;                 a = mfma16(*(const LAS bf16x8*)(kp + 16 * ((unsigned)(4 + g) ^ (key & 7))), qf[1], a);
;                 sc[j][kt] = a; } }
.LBB0_301:
	s_add_i32 s48, s52, s76
	s_lshl_b64 s[26:27], s[48:49], 6
	v_lshl_add_u64 v[52:53], s[26:27], 0, v[46:47]
	v_mov_b64_e32 v[18:19], v[26:27]
	v_mov_b64_e32 v[22:23], v[30:31]
	v_lshlrev_b64 v[34:35], 10, v[52:53]
	v_lshl_add_u64 v[242:243], v[48:49], 0, v[34:35]
	global_load_dwordx2 v[244:245], v[242:243], off
	global_load_dwordx2 v[246:247], v[242:243], off offset:32
	global_load_dwordx2 v[248:249], v[242:243], off offset:64
	global_load_dwordx2 v[242:243], v[242:243], off offset:96
	s_andn2_b64 vcc, exec, s[16:17]
	v_mov_b64_e32 v[20:21], v[28:29]
	v_mov_b64_e32 v[24:25], v[32:33]
	s_cbranch_vccnz .LBB0_303
	v_lshl_add_u64 v[18:19], s[42:43], 0, v[34:35]
	s_mov_b32 s11, s49
	v_lshl_add_u64 v[18:19], v[18:19], 0, s[10:11]
	v_lshl_add_u64 v[18:19], v[18:19], 0, v[70:71]
	v_lshl_add_u64 v[20:21], v[18:19], 0, s[50:51]
	v_add_co_u32_e32 v18, vcc, 0x20000, v18
	s_nop 1
	v_addc_co_u32_e32 v19, vcc, 0, v19, vcc
	global_load_dwordx4 v[22:25], v[18:19], off
	s_nop 0
	global_load_dwordx4 v[18:21], v[20:21], off offset:64
.LBB0_303:
	s_max_i32 s11, s21, 4
	s_add_i32 s11, s11, -4
	s_min_u32 s11, s11, s77
	s_add_i32 s11, s11, s20
	s_mulk_i32 s11, 0x7c
	s_add_i32 s11, s11, 0
	s_add_i32 s15, s11, 0x24000
	v_lshl_add_u32 v172, v63, 2, s15
	v_lshl_add_u32 v173, v65, 2, s15
	ds_read2_b32 v[44:45], v172 offset0:217 offset1:248
	ds_read2_b32 v[54:55], v173 offset0:217 offset1:248
	v_lshl_add_u32 v176, v96, 2, s15
	v_lshl_add_u32 v178, v98, 2, s15
	v_lshl_add_u32 v181, v100, 2, s15
	v_lshl_add_u32 v184, v155, 2, s15
	v_lshl_add_u32 v186, v157, 2, s15
	v_add_u32_e32 v226, 0x400, v172
	v_add_u32_e32 v227, 0x400, v173
	v_add_u32_e32 v228, 0x400, v176
	v_add_u32_e32 v229, 0x400, v178
	s_max_i32 s13, s48, 4
	ds_read2_b32 v[56:57], v176 offset0:217 offset1:248
	s_waitcnt lgkmcnt(2)
	v_add_f32_e32 v36, v62, v44
	s_waitcnt lgkmcnt(1)
	v_add_f32_e32 v37, v64, v54
	ds_read2_b32 v[58:59], v178 offset0:217 offset1:248
	ds_read2_b32 v[60:61], v181 offset0:217 offset1:248
	ds_read2_b32 v[166:167], v184 offset0:217 offset1:248
	ds_read2_b32 v[168:169], v186 offset0:217 offset1:248
	v_add_f32_e32 v54, v62, v45
	ds_read2_b32 v[44:45], v226 offset0:23 offset1:54
	ds_read2_b32 v[174:175], v227 offset0:23 offset1:54
	ds_read2_b32 v[176:177], v228 offset0:23 offset1:54
	ds_read2_b32 v[178:179], v229 offset0:23 offset1:54
	s_add_i32 s13, s13, -4
	s_min_u32 s11, s13, s77
	v_lshl_add_u32 v188, v159, 2, s15
	v_add_u32_e32 v238, 0x400, v186
	s_mul_i32 s13, s11, 57
	v_add_u32_e32 v181, 0x400, v181
	v_add_u32_e32 v236, 0x400, v184
	ds_read2_b32 v[186:187], v238 offset0:23 offset1:54
	v_add_u32_e32 v240, 0x400, v188
	s_bfe_u32 s13, s13, 0x70009
	s_waitcnt lgkmcnt(9)
	v_add_f32_e32 v38, v93, v56
	ds_read2_b32 v[170:171], v188 offset0:217 offset1:248
	s_waitcnt lgkmcnt(8)
	v_add_f32_e32 v40, v99, v60
	s_waitcnt lgkmcnt(7)
	v_add_f32_e32 v41, v101, v166
	s_waitcnt lgkmcnt(6)
	v_add_f32_e32 v42, v156, v168
	v_add_f32_e32 v56, v93, v57
	v_add_f32_e32 v57, v97, v59
	v_add_f32_e32 v59, v101, v167
	v_add_f32_e32 v60, v156, v169
	s_waitcnt lgkmcnt(5)
	v_add_f32_e32 v166, v62, v44
	s_waitcnt lgkmcnt(4)
	v_add_f32_e32 v167, v64, v174
	s_waitcnt lgkmcnt(3)
	v_add_f32_e32 v168, v93, v176
	ds_read2_b32 v[182:183], v181 offset0:23 offset1:54
	ds_read2_b32 v[184:185], v236 offset0:23 offset1:54
	ds_read2_b32 v[188:189], v240 offset0:23 offset1:54
	s_waitcnt lgkmcnt(5)
	v_add_f32_e32 v169, v97, v178
	v_add_f32_e32 v174, v62, v45
	v_add_f32_e32 v176, v93, v177
	v_add_f32_e32 v177, v97, v179
	ds_read2_b32 v[44:45], v226 offset0:85 offset1:116
	ds_read2_b32 v[178:179], v227 offset0:85 offset1:116
	s_mul_i32 s13, s13, 9
	s_sub_i32 s13, s11, s13
	s_and_b32 s13, s13, 0xff
	s_lshl_b32 s25, s13, 13
	s_add_i32 s13, s11, 1
	s_waitcnt lgkmcnt(6)
	v_add_f32_e32 v172, v156, v186
	s_waitcnt lgkmcnt(1)
	v_add_f32_e32 v186, v62, v44
	v_add_u32_e32 v44, s25, v165
	s_and_b32 s15, s13, 0xff
	v_add_f32_e32 v39, v97, v58
	v_add_f32_e32 v58, v99, v61
	v_add_f32_e32 v61, v158, v171
	v_add_f32_e32 v171, v101, v184
	v_add_f32_e32 v184, v156, v187
	s_waitcnt lgkmcnt(0)
	v_add_f32_e32 v187, v64, v178
	v_add_u32_e32 v178, v44, v69
	s_mul_i32 s15, s15, 57
	ds_read_b128 v[190:193], v178
	ds_read2_b32 v[214:215], v228 offset0:85 offset1:116
	ds_read2_b32 v[216:217], v229 offset0:85 offset1:116
	s_bfe_u32 s15, s15, 0x70009
	v_add_u32_e32 v44, v44, v107
	s_mul_i32 s15, s15, 9
	ds_read_b128 v[194:197], v44
	ds_read2_b32 v[218:219], v181 offset0:85 offset1:116
	ds_read_b128 v[198:201], v178 offset:2048
	s_sub_i32 s13, s13, s15
	s_waitcnt lgkmcnt(5)
	v_mfma_f32_16x16x32_bf16 v[36:39], v[190:193], v[30:33], v[36:39]
	s_and_b32 s13, s13, 0xff
	s_lshl_b32 s48, s13, 13
	ds_read2_b32 v[220:221], v236 offset0:85 offset1:116
	ds_read_b128 v[202:205], v44 offset:2048
	v_add_u32_e32 v44, s48, v165
	v_add_u32_e32 v178, v44, v69
	s_waitcnt lgkmcnt(4)
	v_mfma_f32_16x16x32_bf16 v[194:197], v[194:197], v[26:29], v[36:39]
	v_add_f32_e32 v43, v158, v170
	v_add_u32_e32 v44, v44, v107
	s_add_i32 s13, s11, 2
	ds_read_b128 v[36:39], v178
	s_waitcnt lgkmcnt(3)
	v_mfma_f32_16x16x32_bf16 v[40:43], v[198:201], v[30:33], v[40:43]
	ds_read_b128 v[198:201], v44
	s_and_b32 s15, s13, 0xff
	s_mul_i32 s15, s15, 57
	s_bfe_u32 s15, s15, 0x70009
	s_mul_i32 s15, s15, 9
	v_add_f32_e32 v55, v64, v55
	s_waitcnt lgkmcnt(2)
	v_mfma_f32_16x16x32_bf16 v[202:205], v[202:205], v[26:29], v[40:43]
	s_sub_i32 s13, s13, s15
	s_and_b32 s13, s13, 0xff
	s_lshl_b32 s35, s13, 13
	ds_read_b128 v[40:43], v178 offset:2048
	s_waitcnt lgkmcnt(2)
	v_mfma_f32_16x16x32_bf16 v[36:39], v[36:39], v[30:33], v[54:57]
	s_add_i32 s13, s11, 3
	s_and_b32 s15, s13, 0xff
	s_mul_i32 s15, s15, 57
	ds_read_b128 v[54:57], v44 offset:2048
	v_add_u32_e32 v44, s35, v165
	v_add_u32_e32 v178, v44, v69
	s_waitcnt lgkmcnt(2)
; #define LAS __attribute__((address_space(3)))
; __device__ __forceinline__ f32x4 mfma16(bf16x8 a, bf16x8 b, f32x4 c) { return __builtin_amdgcn_mfma_f32_16x16x32_bf16(a, b, c, 0, 0, 0); }
; __device__ __forceinline__ void na_strip(const Params& P, LAS unsigned char* lds, int strip, int hsel, int tid, int lane, int wave) {
;     ...
; #pragma unroll
;         for (int j = 0; j < 8; ++j) { const LAS float* rpj = rp + (start + j - myr + 7) * 31;
; #pragma unroll
;             for (int kt = 0; kt < 2; ++kt)
; #pragma unroll
;                 for (int i = 0; i < 4; ++i) sc[j][kt][i] = rpj[bofs[kt][i]] + msk[kt][i]; }
; #pragma unroll
;         for (int j = 0; j < 8; ++j) { const LAS unsigned char* kt_ = lds + NA_KR + (unsigned)((start + j) % 9) * 8192u;
; #pragma unroll
;             for (int kt = 0; kt < 2; ++kt) { const unsigned key = kstart + 16 * kt + l15; const LAS unsigned char* kp = kt_ + key * 128;
;                 f32x4 a = sc[j][kt];
;                 a = mfma16(*(const LAS bf16x8*)(kp + 16 * ((unsigned)g ^ (key & 7))), qf[0], a);
;                 a = mfma16(*(const LAS bf16x8*)(kp + 16 * ((unsigned)(4 + g) ^ (key & 7))), qf[1], a);
;                 sc[j][kt] = a; } }
; #pragma unroll
;         for (int j = 0; j < 8; ++j)
; #pragma unroll
;             for (int kt = 0; kt < 2; ++kt)
; #pragma unroll
;                 for (int i = 0; i < 4; ++i) sc[j][kt][i] = __builtin_amdgcn_exp2f(sc[j][kt][i]);
	v_mfma_f32_16x16x32_bf16 v[198:201], v[198:201], v[26:29], v[36:39]
	v_add_u32_e32 v44, v44, v107
	ds_read_b128 v[206:209], v44
	s_bfe_u32 s15, s15, 0x70009
	ds_read_b128 v[36:39], v178
	s_waitcnt lgkmcnt(3)
	v_mfma_f32_16x16x32_bf16 v[40:43], v[40:43], v[30:33], v[58:61]
	s_mul_i32 s15, s15, 9
	s_sub_i32 s13, s13, s15
	s_and_b32 s13, s13, 0xff
	s_waitcnt lgkmcnt(2)
	v_mfma_f32_16x16x32_bf16 v[210:213], v[54:57], v[26:29], v[40:43]
	s_lshl_b32 s17, s13, 13
	v_add_f32_e32 v58, v62, v45
	v_add_f32_e32 v170, v99, v182
	ds_read_b128 v[40:43], v178 offset:2048
	s_waitcnt lgkmcnt(1)
	v_mfma_f32_16x16x32_bf16 v[36:39], v[36:39], v[30:33], v[166:169]
	v_add_f32_e32 v173, v158, v188
	v_add_f32_e32 v188, v93, v214
	s_add_i32 s13, s11, 4
	ds_read_b128 v[166:169], v44 offset:2048
	v_add_u32_e32 v44, s17, v165
	v_add_u32_e32 v45, v44, v69
	v_mfma_f32_16x16x32_bf16 v[206:209], v[206:209], v[26:29], v[36:39]
	v_add_u32_e32 v214, v44, v107
	s_and_b32 s15, s13, 0xff
	s_mul_i32 s15, s15, 57
	ds_read_b128 v[36:39], v45
	s_waitcnt lgkmcnt(2)
	v_mfma_f32_16x16x32_bf16 v[40:43], v[40:43], v[30:33], v[170:173]
	s_bfe_u32 s15, s15, 0x70009
	s_mul_i32 s15, s15, 9
	v_add_f32_e32 v175, v64, v175
	ds_read_b128 v[170:173], v214
	s_waitcnt lgkmcnt(2)
	v_mfma_f32_16x16x32_bf16 v[166:169], v[166:169], v[26:29], v[40:43]
	s_sub_i32 s13, s13, s15
	s_and_b32 s13, s13, 0xff
	s_lshl_b32 s16, s13, 13
	ds_read_b128 v[40:43], v45 offset:2048
	s_waitcnt lgkmcnt(2)
	v_mfma_f32_16x16x32_bf16 v[36:39], v[36:39], v[30:33], v[174:177]
	ds_read2_b32 v[222:223], v238 offset0:85 offset1:116
	ds_read2_b32 v[224:225], v240 offset0:85 offset1:116
	v_add_f32_e32 v59, v64, v179
	ds_read2_b32 v[44:45], v226 offset0:147 offset1:178
	ds_read2_b32 v[178:179], v227 offset0:147 offset1:178
	ds_read_b128 v[174:177], v214 offset:2048
	v_add_u32_e32 v214, s16, v165
	v_add_f32_e32 v60, v93, v215
	v_add_u32_e32 v215, v214, v69
	s_waitcnt lgkmcnt(6)
	v_mfma_f32_16x16x32_bf16 v[170:173], v[170:173], v[26:29], v[36:39]
	v_add_f32_e32 v182, v99, v183
	v_add_f32_e32 v183, v101, v185
	v_add_f32_e32 v185, v158, v189
	ds_read_b128 v[36:39], v215
	v_add_f32_e32 v190, v99, v218
	v_add_u32_e32 v218, v214, v107
	s_add_i32 s13, s11, 5
	s_waitcnt lgkmcnt(6)
	v_mfma_f32_16x16x32_bf16 v[40:43], v[40:43], v[30:33], v[182:185]
	s_and_b32 s15, s13, 0xff
	s_mul_i32 s15, s15, 57
	s_bfe_u32 s15, s15, 0x70009
	ds_read_b128 v[182:185], v218
	s_mul_i32 s15, s15, 9
	v_add_f32_e32 v189, v97, v216
	v_add_f32_e32 v61, v97, v217
	ds_read_b128 v[214:217], v215 offset:2048
	s_sub_i32 s13, s13, s15
	s_waitcnt lgkmcnt(2)
	v_mfma_f32_16x16x32_bf16 v[36:39], v[36:39], v[30:33], v[186:189]
	s_and_b32 s13, s13, 0xff
	s_lshl_b32 s15, s13, 13
	ds_read2_b32 v[230:231], v228 offset0:147 offset1:178
	v_mfma_f32_16x16x32_bf16 v[174:177], v[174:177], v[26:29], v[40:43]
	ds_read2_b32 v[232:233], v229 offset0:147 offset1:178
	ds_read_b128 v[186:189], v218 offset:2048
	v_add_f32_e32 v191, v101, v220
	v_add_u32_e32 v43, s15, v165
	v_add_f32_e32 v40, v62, v44
	v_add_u32_e32 v44, v43, v69
	s_waitcnt lgkmcnt(4)
	v_mfma_f32_16x16x32_bf16 v[182:185], v[182:185], v[26:29], v[36:39]
	v_add_f32_e32 v192, v156, v222
	v_add_f32_e32 v193, v158, v224
	v_add_f32_e32 v41, v64, v178
	ds_read_b128 v[36:39], v44
	v_add_u32_e32 v178, v43, v107
	s_add_i32 s13, s11, 6
	s_waitcnt lgkmcnt(4)
	v_mfma_f32_16x16x32_bf16 v[190:193], v[214:217], v[30:33], v[190:193]
	ds_read_b128 v[214:217], v178
	s_and_b32 s26, s13, 0xff
	v_add_f32_e32 v54, v99, v219
	v_add_f32_e32 v55, v101, v221
	ds_read_b128 v[218:221], v44 offset:2048
	s_mul_i32 s26, s26, 57
	s_bfe_u32 s26, s26, 0x70009
	s_mul_i32 s26, s26, 9
	s_sub_i32 s13, s13, s26
	s_waitcnt lgkmcnt(2)
	v_mfma_f32_16x16x32_bf16 v[36:39], v[36:39], v[30:33], v[58:61]
	s_and_b32 s13, s13, 0xff
	s_lshl_b32 s13, s13, 13
	v_add_u32_e32 v44, s13, v165
	ds_read2_b32 v[234:235], v181 offset0:147 offset1:178
	ds_read2_b32 v[236:237], v236 offset0:147 offset1:178
	ds_read2_b32 v[238:239], v238 offset0:147 offset1:178
	ds_read_b128 v[58:61], v178 offset:2048
	v_add_u32_e32 v178, v44, v69
	v_add_f32_e32 v56, v156, v223
	v_add_f32_e32 v57, v158, v225
	s_waitcnt lgkmcnt(5)
	v_mfma_f32_16x16x32_bf16 v[214:217], v[214:217], v[26:29], v[36:39]
	v_add_u32_e32 v44, v44, v107
	s_add_i32 s11, s11, 7
	s_and_b32 s26, s11, 0xff
	ds_read_b128 v[36:39], v178
	s_waitcnt lgkmcnt(5)
	v_mfma_f32_16x16x32_bf16 v[54:57], v[218:221], v[30:33], v[54:57]
	ds_read_b128 v[218:221], v44
	ds_read_b128 v[226:229], v44 offset:2048
	s_mul_i32 s26, s26, 57
	s_waitcnt lgkmcnt(3)
	v_mfma_f32_16x16x32_bf16 v[222:225], v[58:61], v[26:29], v[54:57]
	s_bfe_u32 s26, s26, 0x70009
	s_mul_i32 s26, s26, 9
	v_add_f32_e32 v42, v93, v230
	ds_read_b128 v[54:57], v178 offset:2048
	v_add_f32_e32 v43, v97, v232
	ds_read2_b32 v[240:241], v240 offset0:147 offset1:178
	s_sub_i32 s11, s11, s26
	s_waitcnt lgkmcnt(4)
	v_mfma_f32_16x16x32_bf16 v[36:39], v[36:39], v[30:33], v[40:43]
	s_and_b32 s11, s11, 0xff
	s_lshl_b32 s11, s11, 13
	v_add_f32_e32 v58, v62, v45
	v_add_u32_e32 v40, s11, v165
	v_add_u32_e32 v178, v40, v69
	v_mfma_f32_16x16x32_bf16 v[186:189], v[186:189], v[26:29], v[190:193]
	v_add_u32_e32 v181, v40, v107
	v_add_f32_e32 v59, v64, v179
	v_add_f32_e32 v60, v93, v231
	v_add_f32_e32 v190, v99, v234
	v_add_f32_e32 v191, v101, v236
	v_add_f32_e32 v192, v156, v238
	s_waitcnt lgkmcnt(0)
	v_add_f32_e32 v193, v158, v240
	v_mfma_f32_16x16x32_bf16 v[42:45], v[218:221], v[26:29], v[36:39]
	ds_read_b128 v[218:221], v178
	v_add_f32_e32 v61, v97, v233
	v_exp_f32_e32 v230, v182
	v_mfma_f32_16x16x32_bf16 v[36:39], v[54:57], v[30:33], v[190:193]
	ds_read_b128 v[54:57], v181
	v_exp_f32_e32 v231, v183
	v_exp_f32_e32 v232, v184
	ds_read_b128 v[190:193], v178 offset:2048
	v_mfma_f32_16x16x32_bf16 v[38:41], v[226:229], v[26:29], v[36:39]
	ds_read_b128 v[226:229], v181 offset:2048
	v_lshl_add_u64 v[178:179], v[48:49], 0, v[34:35]
	v_exp_f32_e32 v181, v204
	s_waitcnt lgkmcnt(3)
; __device__ __forceinline__ unsigned cvt_pk_bf16(float lo, float hi) { unsigned r; asm volatile("v_cvt_pk_bf16_f32 %0, %1, %2" : "=v"(r) : "v"(lo), "v"(hi)); return r; }
; #define LAS __attribute__((address_space(3)))
; __device__ __forceinline__ s16x4 tr_read(const LAS unsigned char* p) { return __builtin_amdgcn_ds_read_tr16_b64_v4i16((LAS s16x4*)p); }
; __device__ __forceinline__ bf16x8 cat8(s16x4 a, s16x4 b) { return (bf16x8){a[0], a[1], a[2], a[3], b[0], b[1], b[2], b[3]}; }
; __device__ __forceinline__ f32x4 mfma16(bf16x8 a, bf16x8 b, f32x4 c) { return __builtin_amdgcn_mfma_f32_16x16x32_bf16(a, b, c, 0, 0, 0); }
; __device__ __forceinline__ void na_strip(const Params& P, LAS unsigned char* lds, int strip, int hsel, int tid, int lane, int wave) {
;     ...
;         for (int j = 0; j < 8; ++j)
; #pragma unroll
;             for (int kt = 0; kt < 2; ++kt)
; #pragma unroll
;                 for (int i = 0; i < 4; ++i) sc[j][kt][i] = __builtin_amdgcn_exp2f(sc[j][kt][i]);
;         f32x4 o[4], osum = (f32x4){0.f, 0.f, 0.f, 0.f};
; #pragma unroll
;         for (int dt = 0; dt < 4; ++dt) o[dt] = (f32x4){0.f, 0.f, 0.f, 0.f};
;         const bf16x8 ones8 = (bf16x8){0x3f80, 0x3f80, 0x3f80, 0x3f80, 0x3f80, 0x3f80, 0x3f80, 0x3f80};
; #pragma unroll
;         for (int j = 0; j < 8; ++j) {
;             u32x4 pw; pw.x = cvt_pk_bf16(sc[j][0][0], sc[j][0][1]); pw.y = cvt_pk_bf16(sc[j][0][2], sc[j][0][3]); pw.z = cvt_pk_bf16(sc[j][1][0], sc[j][1][1]); pw.w = cvt_pk_bf16(sc[j][1][2], sc[j][1][3]);
;             const bf16x8 pb = __builtin_bit_cast(bf16x8, pw);
;             const LAS unsigned char* vt = lds + NA_VR + (unsigned)((start + j) % 9) * 8192u;
;             const unsigned k0 = kstart + 4 * g + q4, k1 = k0 + 16;
;             const unsigned x0 = 4 * ((k0 >> 1) & 3), x1 = 4 * ((k1 >> 1) & 3);
; #pragma unroll
;             for (int dt = 0; dt < 4; ++dt) {
;                 const bf16x8 va = cat8(tr_read(vt + k0 * 128 + 8 * ((unsigned)(4 * dt + p) ^ x0)), tr_read(vt + k1 * 128 + 8 * ((unsigned)(4 * dt + p) ^ x1)));
;                 o[dt] = mfma16(va, pb, o[dt]); }
;             osum = mfma16(ones8, pb, osum);
;         }
	v_mfma_f32_16x16x32_bf16 v[58:61], v[218:221], v[30:33], v[58:61]
	v_add_f32_e32 v218, v99, v235
	v_add_f32_e32 v219, v101, v237
	v_add_f32_e32 v220, v156, v239
	v_add_f32_e32 v221, v158, v241
	s_waitcnt lgkmcnt(2)
	v_mfma_f32_16x16x32_bf16 v[34:37], v[54:57], v[26:29], v[58:61]
	s_nop 2
	v_exp_f32_e32 v178, v202
	v_exp_f32_e32 v179, v203
	s_waitcnt lgkmcnt(1)
	v_mfma_f32_16x16x32_bf16 v[30:33], v[190:193], v[30:33], v[218:221]
	v_exp_f32_e32 v190, v205
	v_exp_f32_e32 v191, v198
	v_exp_f32_e32 v198, v213
	s_waitcnt lgkmcnt(0)
	v_mfma_f32_16x16x32_bf16 v[26:29], v[226:229], v[26:29], v[30:33]
	v_exp_f32_e32 v213, v169
	v_exp_f32_e32 v192, v199
	v_exp_f32_e32 v220, v172
	v_exp_f32_e32 v30, v194
	v_exp_f32_e32 v31, v195
	v_exp_f32_e32 v32, v196
	v_exp_f32_e32 v33, v197
	v_exp_f32_e32 v195, v210
	v_exp_f32_e32 v196, v211
	v_exp_f32_e32 v197, v212
	v_exp_f32_e32 v210, v166
	v_exp_f32_e32 v211, v167
	v_exp_f32_e32 v212, v168
	v_cvt_pk_bf16_f32 v166, v30, v31
	v_cvt_pk_bf16_f32 v167, v32, v33
	v_cvt_pk_bf16_f32 v168, v178, v179
	v_add_u32_e32 v178, s25, v160
	v_add_u32_e32 v32, v178, v161
	v_cvt_pk_bf16_f32 v169, v181, v190
	ds_read_b64_tr_b16 v[30:31], v32
	ds_read_b64_tr_b16 v[32:33], v32 offset:2048
	v_exp_f32_e32 v228, v176
	v_exp_f32_e32 v233, v185
	v_add_u32_e32 v172, v178, v162
	v_add_u32_e32 v176, v178, v163
	s_waitcnt lgkmcnt(0)
	v_mfma_f32_16x16x32_bf16 v[182:185], v[30:33], v[166:169], 0
	v_add_u32_e32 v30, v178, v164
	v_add_u32_e32 v178, s48, v160
	v_exp_f32_e32 v193, v200
	v_exp_f32_e32 v194, v201
	v_exp_f32_e32 v218, v170
	v_exp_f32_e32 v219, v171
	v_exp_f32_e32 v221, v173
	v_exp_f32_e32 v226, v174
	v_exp_f32_e32 v227, v175
	v_exp_f32_e32 v229, v177
	v_exp_f32_e32 v234, v186
	v_exp_f32_e32 v235, v187
	v_exp_f32_e32 v179, v188
	ds_read_b64_tr_b16 v[170:171], v172
	ds_read_b64_tr_b16 v[172:173], v172 offset:2048
	v_exp_f32_e32 v181, v189
	ds_read_b64_tr_b16 v[174:175], v176
	ds_read_b64_tr_b16 v[176:177], v176 offset:2048
	ds_read_b64_tr_b16 v[186:187], v30
	ds_read_b64_tr_b16 v[188:189], v30 offset:2048
	v_cvt_pk_bf16_f32 v190, v191, v192
	v_cvt_pk_bf16_f32 v191, v193, v194
	v_cvt_pk_bf16_f32 v192, v195, v196
	v_add_u32_e32 v196, v178, v161
	v_cvt_pk_bf16_f32 v193, v197, v198
	ds_read_b64_tr_b16 v[194:195], v196
	ds_read_b64_tr_b16 v[196:197], v196 offset:2048
	s_mov_b32 s26, s24
	s_mov_b32 s27, s24
	s_mov_b32 s25, s24
	v_mov_b64_e32 v[32:33], s[26:27]
	v_add_u32_e32 v200, v178, v162
	v_add_u32_e32 v204, v178, v163
	v_add_u32_e32 v178, v178, v164
	v_mov_b64_e32 v[30:31], s[24:25]
	ds_read_b64_tr_b16 v[198:199], v200
	ds_read_b64_tr_b16 v[200:201], v200 offset:2048
	ds_read_b64_tr_b16 v[202:203], v204
	ds_read_b64_tr_b16 v[204:205], v204 offset:2048
	s_waitcnt lgkmcnt(4)
	v_mfma_f32_16x16x32_bf16 v[182:185], v[194:197], v[190:193], v[182:185]
	ds_read_b64_tr_b16 v[194:195], v178
	ds_read_b64_tr_b16 v[196:197], v178 offset:2048
	v_add_u32_e32 v178, s35, v160
	v_exp_f32_e32 v206, v206
	v_mfma_f32_16x16x32_bf16 v[174:177], v[174:177], v[166:169], 0
	v_exp_f32_e32 v207, v207
	v_exp_f32_e32 v208, v208
	v_exp_f32_e32 v209, v209
	v_mfma_f32_16x16x32_bf16 v[186:189], v[186:189], v[166:169], 0
	v_exp_f32_e32 v214, v214
	v_exp_f32_e32 v215, v215
	v_exp_f32_e32 v216, v216
	v_mfma_f32_16x16x32_bf16 v[170:173], v[170:173], v[166:169], 0
	v_exp_f32_e32 v217, v217
	v_exp_f32_e32 v222, v222
	v_exp_f32_e32 v223, v223
	v_mfma_f32_16x16x32_bf16 v[166:169], v[30:33], v[166:169], 0
	s_and_b64 vcc, exec, s[4:5]
	s_waitcnt lgkmcnt(2)
	v_mfma_f32_16x16x32_bf16 v[174:177], v[202:205], v[190:193], v[174:177]
	v_add_u32_e32 v204, v178, v161
	s_waitcnt lgkmcnt(0)
	v_mfma_f32_16x16x32_bf16 v[186:189], v[194:197], v[190:193], v[186:189]
	v_add_u32_e32 v196, v178, v162
	v_mfma_f32_16x16x32_bf16 v[170:173], v[198:201], v[190:193], v[170:173]
	v_cvt_pk_bf16_f32 v198, v206, v207
	v_cvt_pk_bf16_f32 v199, v208, v209
	v_cvt_pk_bf16_f32 v200, v210, v211
	v_cvt_pk_bf16_f32 v201, v212, v213
	ds_read_b64_tr_b16 v[202:203], v204
	ds_read_b64_tr_b16 v[204:205], v204 offset:2048
	ds_read_b64_tr_b16 v[194:195], v196
	ds_read_b64_tr_b16 v[196:197], v196 offset:2048
	v_mfma_f32_16x16x32_bf16 v[166:169], v[30:33], v[190:193], v[166:169]
	v_add_u32_e32 v192, v178, v163
	ds_read_b64_tr_b16 v[190:191], v192
	ds_read_b64_tr_b16 v[192:193], v192 offset:2048
	v_exp_f32_e32 v208, v42
	v_add_u32_e32 v42, v178, v164
	s_waitcnt lgkmcnt(2)
	v_mfma_f32_16x16x32_bf16 v[170:173], v[194:197], v[198:201], v[170:173]
	ds_read_b64_tr_b16 v[194:195], v42
	ds_read_b64_tr_b16 v[196:197], v42 offset:2048
	v_add_u32_e32 v178, s17, v160
	v_add_u32_e32 v42, v178, v161
	v_mfma_f32_16x16x32_bf16 v[182:185], v[202:205], v[198:201], v[182:185]
	v_exp_f32_e32 v206, v224
	v_exp_f32_e32 v207, v225
	s_waitcnt lgkmcnt(2)
	v_mfma_f32_16x16x32_bf16 v[174:177], v[190:193], v[198:201], v[174:177]
	v_cvt_pk_bf16_f32 v190, v218, v219
	v_cvt_pk_bf16_f32 v191, v220, v221
	v_cvt_pk_bf16_f32 v192, v226, v227
	v_cvt_pk_bf16_f32 v193, v228, v229
	ds_read_b64_tr_b16 v[202:203], v42
	ds_read_b64_tr_b16 v[204:205], v42 offset:2048
	v_add_u32_e32 v42, v178, v162
	s_waitcnt lgkmcnt(2)
	v_mfma_f32_16x16x32_bf16 v[186:189], v[194:197], v[198:201], v[186:189]
	ds_read_b64_tr_b16 v[194:195], v42
	ds_read_b64_tr_b16 v[196:197], v42 offset:2048
	v_add_u32_e32 v42, v178, v163
	v_mfma_f32_16x16x32_bf16 v[166:169], v[30:33], v[198:201], v[166:169]
	ds_read_b64_tr_b16 v[198:199], v42
	ds_read_b64_tr_b16 v[200:201], v42 offset:2048
	s_waitcnt lgkmcnt(4)
	v_mfma_f32_16x16x32_bf16 v[182:185], v[202:205], v[190:193], v[182:185]
	v_exp_f32_e32 v202, v43
	v_exp_f32_e32 v203, v44
	v_exp_f32_e32 v204, v45
	s_waitcnt lgkmcnt(2)
; __device__ __forceinline__ unsigned cvt_pk_bf16(float lo, float hi) { unsigned r; asm volatile("v_cvt_pk_bf16_f32 %0, %1, %2" : "=v"(r) : "v"(lo), "v"(hi)); return r; }
; #define LAS __attribute__((address_space(3)))
; __device__ __forceinline__ s16x4 tr_read(const LAS unsigned char* p) { return __builtin_amdgcn_ds_read_tr16_b64_v4i16((LAS s16x4*)p); }
; __device__ __forceinline__ bf16x8 cat8(s16x4 a, s16x4 b) { return (bf16x8){a[0], a[1], a[2], a[3], b[0], b[1], b[2], b[3]}; }
; __device__ __forceinline__ f32x4 mfma16(bf16x8 a, bf16x8 b, f32x4 c) { return __builtin_amdgcn_mfma_f32_16x16x32_bf16(a, b, c, 0, 0, 0); }
; __device__ __forceinline__ void na_strip(const Params& P, LAS unsigned char* lds, int strip, int hsel, int tid, int lane, int wave) {
;     ...
; #pragma unroll
;         for (int j = 0; j < 8; ++j) {
;             u32x4 pw; pw.x = cvt_pk_bf16(sc[j][0][0], sc[j][0][1]); pw.y = cvt_pk_bf16(sc[j][0][2], sc[j][0][3]); pw.z = cvt_pk_bf16(sc[j][1][0], sc[j][1][1]); pw.w = cvt_pk_bf16(sc[j][1][2], sc[j][1][3]);
;             const bf16x8 pb = __builtin_bit_cast(bf16x8, pw);
;             const LAS unsigned char* vt = lds + NA_VR + (unsigned)((start + j) % 9) * 8192u;
;             const unsigned k0 = kstart + 4 * g + q4, k1 = k0 + 16;
;             const unsigned x0 = 4 * ((k0 >> 1) & 3), x1 = 4 * ((k1 >> 1) & 3);
; #pragma unroll
;             for (int dt = 0; dt < 4; ++dt) {
;                 const bf16x8 va = cat8(tr_read(vt + k0 * 128 + 8 * ((unsigned)(4 * dt + p) ^ x0)), tr_read(vt + k1 * 128 + 8 * ((unsigned)(4 * dt + p) ^ x1)));
;                 o[dt] = mfma16(va, pb, o[dt]); }
;             osum = mfma16(ones8, pb, osum);
;         }
	v_mfma_f32_16x16x32_bf16 v[42:45], v[194:197], v[190:193], v[170:173]
	v_exp_f32_e32 v205, v40
	s_nop 1
	v_add_u32_e32 v172, v178, v164
	ds_read_b64_tr_b16 v[170:171], v172
	ds_read_b64_tr_b16 v[172:173], v172 offset:2048
	v_add_u32_e32 v178, s16, v160
	v_cvt_pk_bf16_f32 v194, v230, v231
	v_cvt_pk_bf16_f32 v195, v232, v233
	v_cvt_pk_bf16_f32 v196, v234, v235
	v_cvt_pk_bf16_f32 v197, v179, v181
	v_add_u32_e32 v179, v178, v161
	s_waitcnt lgkmcnt(2)
	v_mfma_f32_16x16x32_bf16 v[174:177], v[198:201], v[190:193], v[174:177]
	ds_read_b64_tr_b16 v[198:199], v179
	ds_read_b64_tr_b16 v[200:201], v179 offset:2048
	v_add_u32_e32 v179, v178, v162
	v_exp_f32_e32 v181, v39
	s_waitcnt lgkmcnt(2)
	v_mfma_f32_16x16x32_bf16 v[170:173], v[170:173], v[190:193], v[186:189]
	s_nop 2
	ds_read_b64_tr_b16 v[186:187], v179
	ds_read_b64_tr_b16 v[188:189], v179 offset:2048
	v_add_u32_e32 v179, v178, v163
	v_mfma_f32_16x16x32_bf16 v[166:169], v[30:33], v[190:193], v[166:169]
	ds_read_b64_tr_b16 v[190:191], v179
	ds_read_b64_tr_b16 v[192:193], v179 offset:2048
	v_exp_f32_e32 v179, v38
	v_add_u32_e32 v38, v178, v164
	s_waitcnt lgkmcnt(2)
	v_mfma_f32_16x16x32_bf16 v[42:45], v[186:189], v[194:197], v[42:45]
	ds_read_b64_tr_b16 v[186:187], v38
	ds_read_b64_tr_b16 v[188:189], v38 offset:2048
	v_add_u32_e32 v178, s15, v160
	v_add_u32_e32 v38, v178, v161
	v_mfma_f32_16x16x32_bf16 v[182:185], v[198:201], v[194:197], v[182:185]
	s_waitcnt lgkmcnt(2)
	v_mfma_f32_16x16x32_bf16 v[174:177], v[190:193], v[194:197], v[174:177]
	v_cvt_pk_bf16_f32 v190, v214, v215
	v_cvt_pk_bf16_f32 v191, v216, v217
	v_cvt_pk_bf16_f32 v192, v222, v223
	v_cvt_pk_bf16_f32 v193, v206, v207
	ds_read_b64_tr_b16 v[198:199], v38
	ds_read_b64_tr_b16 v[200:201], v38 offset:2048
	v_add_u32_e32 v38, v178, v162
	s_waitcnt lgkmcnt(2)
	v_mfma_f32_16x16x32_bf16 v[170:173], v[186:189], v[194:197], v[170:173]
	ds_read_b64_tr_b16 v[186:187], v38
	ds_read_b64_tr_b16 v[188:189], v38 offset:2048
	v_add_u32_e32 v38, v178, v163
	v_mfma_f32_16x16x32_bf16 v[166:169], v[30:33], v[194:197], v[166:169]
	ds_read_b64_tr_b16 v[194:195], v38
	ds_read_b64_tr_b16 v[196:197], v38 offset:2048
	s_waitcnt lgkmcnt(4)
	v_mfma_f32_16x16x32_bf16 v[182:185], v[198:201], v[190:193], v[182:185]
	v_exp_f32_e32 v199, v34
	v_add_u32_e32 v34, v178, v164
	v_exp_f32_e32 v198, v41
	s_waitcnt lgkmcnt(2)
	v_mfma_f32_16x16x32_bf16 v[38:41], v[186:189], v[190:193], v[42:45]
	s_nop 2
	ds_read_b64_tr_b16 v[42:43], v34
	ds_read_b64_tr_b16 v[44:45], v34 offset:2048
	v_add_u32_e32 v34, s13, v160
	v_exp_f32_e32 v200, v35
	v_add_u32_e32 v35, v34, v161
	s_waitcnt lgkmcnt(2)
	v_mfma_f32_16x16x32_bf16 v[174:177], v[194:197], v[190:193], v[174:177]
	v_cvt_pk_bf16_f32 v186, v208, v202
	v_cvt_pk_bf16_f32 v187, v203, v204
	v_cvt_pk_bf16_f32 v188, v179, v181
	v_cvt_pk_bf16_f32 v189, v205, v198
	ds_read_b64_tr_b16 v[194:195], v35
	ds_read_b64_tr_b16 v[196:197], v35 offset:2048
	v_add_u32_e32 v35, v34, v162
	s_waitcnt lgkmcnt(2)
	v_mfma_f32_16x16x32_bf16 v[42:45], v[42:45], v[190:193], v[170:173]
	s_nop 2
	ds_read_b64_tr_b16 v[170:171], v35
	ds_read_b64_tr_b16 v[172:173], v35 offset:2048
	v_add_u32_e32 v35, v34, v163
	v_add_u32_e32 v34, v34, v164
	v_mfma_f32_16x16x32_bf16 v[166:169], v[30:33], v[190:193], v[166:169]
	ds_read_b64_tr_b16 v[190:191], v35
	ds_read_b64_tr_b16 v[192:193], v35 offset:2048
	v_add_u32_e32 v178, s11, v160
	v_add_u32_e32 v179, v178, v163
	s_waitcnt lgkmcnt(4)
	v_mfma_f32_16x16x32_bf16 v[182:185], v[194:197], v[186:189], v[182:185]
	ds_read_b64_tr_b16 v[194:195], v34
	ds_read_b64_tr_b16 v[196:197], v34 offset:2048
	s_waitcnt lgkmcnt(4)
	v_mfma_f32_16x16x32_bf16 v[38:41], v[170:173], v[186:189], v[38:41]
	v_exp_f32_e32 v172, v26
	v_exp_f32_e32 v170, v36
	v_exp_f32_e32 v171, v37
	v_mfma_f32_16x16x32_bf16 v[166:169], v[30:33], v[186:189], v[166:169]
	v_exp_f32_e32 v173, v27
	s_waitcnt lgkmcnt(2)
; __device__ __forceinline__ unsigned cvt_pk_bf16(float lo, float hi) { unsigned r; asm volatile("v_cvt_pk_bf16_f32 %0, %1, %2" : "=v"(r) : "v"(lo), "v"(hi)); return r; }
; #define LAS __attribute__((address_space(3)))
; __device__ __forceinline__ float bf_lo(unsigned u) { return __uint_as_float(u << 16); }
; __device__ __forceinline__ float bf_hi(unsigned u) { return __uint_as_float(u & 0xffff0000u); }
; #define LBAR() asm volatile("s_waitcnt lgkmcnt(0)\n\ts_barrier" ::: "memory")
; __device__ __forceinline__ void na_strip(const Params& P, LAS unsigned char* lds, int strip, int hsel, int tid, int lane, int wave) {
;     ...
;         const float inv = __builtin_amdgcn_rcpf(osum[0]);
; #pragma unroll
;         for (int dt = 0; dt < 4; ++dt) {
;             u32x2 w; w.x = cvt_pk_bf16(o[dt][0] * inv * bf_lo(gv[dt].x), o[dt][1] * inv * bf_hi(gv[dt].x)); w.y = cvt_pk_bf16(o[dt][2] * inv * bf_lo(gv[dt].y), o[dt][3] * inv * bf_hi(gv[dt].y));
;             *(u32x2*)(MIX + tq * DM + h * 64 + 16 * dt + 4 * g) = w; }
;         LBAR();
;         if (need0) { const unsigned sl = (unsigned)(nr0 % 9) * 8192u; *(LAS u32x4*)(lds + sl + kdst) = nk0; *(LAS u32x4*)(lds + sl + vdst) = nv0; }
;         if (need1) { const unsigned sl = (unsigned)(nr1 % 9) * 8192u; *(LAS u32x4*)(lds + sl + kdst) = nk1; *(LAS u32x4*)(lds + sl + vdst) = nv1; }
	v_mfma_f32_16x16x32_bf16 v[34:37], v[190:193], v[186:189], v[174:177]
	s_nop 2
	v_exp_f32_e32 v174, v28
	v_exp_f32_e32 v175, v29
	s_waitcnt lgkmcnt(0)
	v_mfma_f32_16x16x32_bf16 v[26:29], v[194:197], v[186:189], v[42:45]
	v_cvt_pk_bf16_f32 v42, v199, v200
	v_cvt_pk_bf16_f32 v43, v170, v171
	v_cvt_pk_bf16_f32 v44, v172, v173
	v_add_u32_e32 v172, v178, v161
	v_add_u32_e32 v176, v178, v162
	v_cvt_pk_bf16_f32 v45, v174, v175
	ds_read_b64_tr_b16 v[170:171], v172
	ds_read_b64_tr_b16 v[172:173], v172 offset:2048
	ds_read_b64_tr_b16 v[174:175], v176
	ds_read_b64_tr_b16 v[176:177], v176 offset:2048
	v_mfma_f32_16x16x32_bf16 v[30:33], v[30:33], v[42:45], v[166:169]
	s_waitcnt lgkmcnt(0)
	v_mfma_f32_16x16x32_bf16 v[38:41], v[174:177], v[42:45], v[38:41]
	v_add_u32_e32 v176, v178, v164
	s_nop 4
	v_rcp_f32_e32 v166, v30
	s_waitcnt vmcnt(0)
	v_lshlrev_b32_e32 v33, 16, v244
	v_mfma_f32_16x16x32_bf16 v[170:173], v[170:173], v[42:45], v[182:185]
	s_nop 2
	ds_read_b64_tr_b16 v[182:183], v179
	ds_read_b64_tr_b16 v[184:185], v179 offset:2048
	ds_read_b64_tr_b16 v[174:175], v176
	ds_read_b64_tr_b16 v[176:177], v176 offset:2048
	v_lshlrev_b64 v[30:31], 11, v[52:53]
	v_mul_f32_e32 v32, v170, v166
	s_waitcnt lgkmcnt(2)
	v_mfma_f32_16x16x32_bf16 v[34:37], v[182:185], v[42:45], v[34:37]
	v_mul_f32_e32 v32, v32, v33
	v_mul_f32_e32 v33, v171, v166
	v_lshl_add_u64 v[30:31], v[50:51], 0, v[30:31]
	s_waitcnt lgkmcnt(0)
	v_mfma_f32_16x16x32_bf16 v[26:29], v[174:177], v[42:45], v[26:29]
	v_and_b32_e32 v42, 0xffff0000, v244
	v_mul_f32_e32 v33, v33, v42
	v_cvt_pk_bf16_f32 v32, v32, v33
	v_mul_f32_e32 v33, v172, v166
	v_lshlrev_b32_e32 v42, 16, v245
	v_mul_f32_e32 v33, v33, v42
	v_mul_f32_e32 v42, v173, v166
	v_and_b32_e32 v43, 0xffff0000, v245
	v_mul_f32_e32 v42, v42, v43
	v_cvt_pk_bf16_f32 v33, v33, v42
	global_store_dwordx2 v[30:31], v[32:33], off
	v_mul_f32_e32 v32, v38, v166
	s_waitcnt vmcnt(3)
	v_lshlrev_b32_e32 v33, 16, v246
	v_mul_f32_e32 v32, v32, v33
	v_mul_f32_e32 v33, v39, v166
	v_and_b32_e32 v38, 0xffff0000, v246
	v_mul_f32_e32 v33, v33, v38
	v_cvt_pk_bf16_f32 v32, v32, v33
	v_mul_f32_e32 v33, v40, v166
	v_lshlrev_b32_e32 v38, 16, v247
	v_mul_f32_e32 v33, v33, v38
	v_mul_f32_e32 v38, v41, v166
	v_and_b32_e32 v39, 0xffff0000, v247
	v_mul_f32_e32 v38, v38, v39
	v_cvt_pk_bf16_f32 v33, v33, v38
	global_store_dwordx2 v[30:31], v[32:33], off offset:32
	v_mul_f32_e32 v32, v34, v166
	s_waitcnt vmcnt(3)
	v_lshlrev_b32_e32 v33, 16, v248
	v_mul_f32_e32 v32, v32, v33
	v_mul_f32_e32 v33, v35, v166
	v_and_b32_e32 v34, 0xffff0000, v248
	v_mul_f32_e32 v33, v33, v34
	v_cvt_pk_bf16_f32 v32, v32, v33
	v_mul_f32_e32 v33, v36, v166
	v_lshlrev_b32_e32 v34, 16, v249
	v_mul_f32_e32 v33, v33, v34
	v_mul_f32_e32 v34, v37, v166
	v_and_b32_e32 v35, 0xffff0000, v249
	v_mul_f32_e32 v34, v34, v35
	v_cvt_pk_bf16_f32 v33, v33, v34
	global_store_dwordx2 v[30:31], v[32:33], off offset:64
	v_mul_f32_e32 v26, v26, v166
	s_waitcnt vmcnt(3)
	v_lshlrev_b32_e32 v32, 16, v242
	v_mul_f32_e32 v26, v26, v32
	v_mul_f32_e32 v27, v27, v166
	v_and_b32_e32 v32, 0xffff0000, v242
	v_mul_f32_e32 v27, v27, v32
	v_cvt_pk_bf16_f32 v26, v26, v27
	v_mul_f32_e32 v27, v28, v166
	v_lshlrev_b32_e32 v28, 16, v243
	v_mul_f32_e32 v27, v27, v28
	v_mul_f32_e32 v28, v29, v166
	v_and_b32_e32 v29, 0xffff0000, v243
	v_mul_f32_e32 v28, v28, v29
	v_cvt_pk_bf16_f32 v27, v27, v28
	global_store_dwordx2 v[30:31], v[26:27], off offset:96
	s_waitcnt lgkmcnt(0)
	s_barrier
	s_cbranch_vccnz .LBB0_305
	s_mul_i32 s4, s12, 0xe38f
	s_lshr_b32 s4, s4, 19
	s_mul_i32 s4, s4, 9
	s_sub_i32 s4, s12, s4
	s_and_b32 s4, s4, 0xffff
	s_lshl_b32 s4, s4, 13
	s_add_i32 s4, s4, 0
	v_add_u32_e32 v26, s4, v67
	ds_write_b128 v26, v[2:5]
	v_add_u32_e32 v26, s4, v81
	ds_write_b128 v26, v[6:9]
